# stack + final LayerNorm: next-row prefetch as global loads (off lgkmcnt) and counted wait vmcnt(8) instead of vmcnt(0) after the 8 row stores
# baseline (speedup 1.0000x reference)
; __device__ __forceinline__ float bf_lo(unsigned w) { return __uint_as_float(w << 16); }
; __device__ __forceinline__ float bf_hi(unsigned w) { return __uint_as_float(w & 0xffff0000u); }
; __device__ __forceinline__ float wave_sum(float v, int lane) { for (int o = 32; o >= 1; o >>= 1) v += shflx(v, o, lane); return v; }
; __device__ __forceinline__ void ln_final(const bf16_t* tb, float* out, const float* __restrict__ g, const float* __restrict__ b, const int tid, const int bid) {
;     ...
;     for (; row < M; row += gridDim.x * 8) {
;         f32x4 v[8]; float s = 0.f;
; #pragma unroll
;         for (int i = 0; i < 4; ++i) {
;             v[2 * i] = (f32x4){bf_lo(wn[i].x), bf_hi(wn[i].x), bf_lo(wn[i].y), bf_hi(wn[i].y)}; v[2 * i + 1] = (f32x4){bf_lo(wn[i].z), bf_hi(wn[i].z), bf_lo(wn[i].w), bf_hi(wn[i].w)};
;             s += ((v[2 * i][0] + v[2 * i][1]) + (v[2 * i][2] + v[2 * i][3])) + ((v[2 * i + 1][0] + v[2 * i + 1][1]) + (v[2 * i + 1][2] + v[2 * i + 1][3]));
;         }
;         const int rn = row + gridDim.x * 8;
;         if (rn < M) {
; #pragma unroll
;             for (int i = 0; i < 4; ++i) wn[i] = *(const u32x4*)(tb + (size_t)rn * D + i * 512 + lane * 8);
;         }
;         const float mean = wave_sum(s, lane) * (1.f / D); float q = 0.f;
; #pragma unroll
;         for (int i = 0; i < 8; ++i) { const f32x4 d = v[i] - mean; q += (d[0] * d[0] + d[1] * d[1]) + (d[2] * d[2] + d[3] * d[3]); }
;         const float rstd = __builtin_amdgcn_rsqf(wave_sum(q, lane) * (1.f / D) + LN_EPS);
.LBB0_92:
	s_or_b64 exec, exec, s[8:9]
	v_lshlrev_b32_e32 v126, 16, v94
	v_and_b32_e32 v127, 0xffff0000, v94
	v_lshlrev_b32_e32 v128, 16, v95
	v_and_b32_e32 v129, 0xffff0000, v95
	v_lshlrev_b32_e32 v122, 16, v96
	v_and_b32_e32 v123, 0xffff0000, v96
	v_lshlrev_b32_e32 v124, 16, v97
	v_and_b32_e32 v125, 0xffff0000, v97
	v_add_f32_e32 v94, v126, v127
	v_add_f32_e32 v95, v128, v129
	v_lshlrev_b32_e32 v118, 16, v90
	v_and_b32_e32 v119, 0xffff0000, v90
	v_lshlrev_b32_e32 v120, 16, v91
	v_and_b32_e32 v121, 0xffff0000, v91
	v_add_f32_e32 v94, v94, v95
	v_add_f32_e32 v95, v122, v123
	v_add_f32_e32 v96, v124, v125
	v_lshlrev_b32_e32 v114, 16, v92
	v_and_b32_e32 v115, 0xffff0000, v92
	v_lshlrev_b32_e32 v116, 16, v93
	v_and_b32_e32 v117, 0xffff0000, v93
	v_add_f32_e32 v90, v118, v119
	v_add_f32_e32 v91, v120, v121
	v_add_f32_e32 v95, v95, v96
	v_add_f32_e32 v90, v90, v91
	v_add_f32_e32 v91, v114, v115
	v_add_f32_e32 v92, v116, v117
	v_add_f32_e32 v94, v95, v94
	v_add_f32_e32 v91, v91, v92
	v_add_f32_e32 v94, 0, v94
	v_add_f32_e32 v90, v91, v90
	v_lshlrev_b32_e32 v112, 16, v86
	v_and_b32_e32 v113, 0xffff0000, v86
	v_lshlrev_b32_e32 v96, 16, v87
	v_and_b32_e32 v97, 0xffff0000, v87
	v_add_f32_e32 v90, v90, v94
	v_lshlrev_b32_e32 v92, 16, v88
	v_and_b32_e32 v93, 0xffff0000, v88
	v_lshlrev_b32_e32 v94, 16, v89
	v_and_b32_e32 v95, 0xffff0000, v89
	v_add_f32_e32 v86, v112, v113
	v_add_f32_e32 v87, v96, v97
	v_add_f32_e32 v86, v86, v87
	v_add_f32_e32 v87, v92, v93
	v_add_f32_e32 v88, v94, v95
	v_add_f32_e32 v87, v87, v88
	v_add_f32_e32 v86, v87, v86
	v_add_f32_e32 v99, v86, v90
	v_lshlrev_b32_e32 v88, 16, v82
	v_and_b32_e32 v89, 0xffff0000, v82
	v_lshlrev_b32_e32 v90, 16, v83
	v_and_b32_e32 v91, 0xffff0000, v83
	v_lshlrev_b32_e32 v86, 16, v84
	v_and_b32_e32 v87, 0xffff0000, v84
	v_lshlrev_b32_e32 v82, 16, v85
	v_and_b32_e32 v83, 0xffff0000, v85
	v_add_f32_e32 v84, v88, v89
	v_add_f32_e32 v85, v90, v91
	v_add_f32_e32 v84, v84, v85
	v_add_f32_e32 v85, v86, v87
	v_add_f32_e32 v103, v82, v83
	v_add_f32_e32 v85, v85, v103
	v_add_f32_e32 v84, v85, v84
	v_add_f32_e32 v84, v84, v99
	ds_bpermute_b32 v85, v130, v84
	s_and_b64 s[0:1], exec, vcc
	s_or_b64 s[6:7], s[0:1], s[6:7]
	s_load_dwordx2 s[0:1], s[68:69], 0xb8
	v_mov_b32_e32 v103, v1
	s_waitcnt lgkmcnt(0)
	v_add_f32_e32 v84, v84, v85
	ds_bpermute_b32 v85, v131, v84
	v_mov_b32_e32 v105, v1
	v_mov_b32_e32 v107, v1
	v_mov_b32_e32 v109, v1
	s_waitcnt lgkmcnt(0)
	v_add_f32_e32 v84, v84, v85
	ds_bpermute_b32 v85, v132, v84
	s_waitcnt lgkmcnt(0)
	v_add_f32_e32 v84, v84, v85
	ds_bpermute_b32 v85, v133, v84
	s_waitcnt lgkmcnt(0)
	v_add_f32_e32 v84, v84, v85
	ds_bpermute_b32 v85, v134, v84
	s_waitcnt lgkmcnt(0)
	v_add_f32_e32 v84, v84, v85
	ds_bpermute_b32 v85, v135, v84
	s_waitcnt lgkmcnt(0)
	v_add_f32_e32 v99, v84, v85
	v_fmac_f32_e32 v127, 0xba000000, v99
	v_fmac_f32_e32 v123, 0xba000000, v99
	v_fmac_f32_e32 v129, 0xba000000, v99
	v_fmac_f32_e32 v126, 0xba000000, v99
	v_fmac_f32_e32 v125, 0xba000000, v99
	v_fmac_f32_e32 v122, 0xba000000, v99
	v_mov_b32_e32 v136, v127
	v_mov_b32_e32 v137, v123
	v_fmac_f32_e32 v128, 0xba000000, v99
	v_fmac_f32_e32 v124, 0xba000000, v99
	v_mov_b32_e32 v84, v126
	v_mov_b32_e32 v85, v122
	v_pk_mul_f32 v[136:137], v[136:137], v[136:137]
	v_mov_b32_e32 v138, v129
	v_mov_b32_e32 v139, v125
	v_pk_fma_f32 v[84:85], v[84:85], v[84:85], v[136:137]
	v_mov_b32_e32 v136, v128
	v_mov_b32_e32 v137, v124
	v_pk_mul_f32 v[138:139], v[138:139], v[138:139]
	v_fmac_f32_e32 v119, 0xba000000, v99
	v_pk_fma_f32 v[136:137], v[136:137], v[136:137], v[138:139]
	v_fmac_f32_e32 v118, 0xba000000, v99
	v_pk_add_f32 v[84:85], v[84:85], v[136:137]
	v_fmac_f32_e32 v121, 0xba000000, v99
	v_fmac_f32_e32 v120, 0xba000000, v99
	v_pk_add_f32 v[84:85], v[84:85], v[84:85] op_sel_hi:[0,1]
	v_pk_mul_f32 v[136:137], v[120:121], v[120:121]
	v_pk_mul_f32 v[138:139], v[118:119], v[118:119]
	v_fmac_f32_e32 v114, 0xba000000, v99
	v_pk_mov_b32 v[140:141], v[138:139], v[136:137] op_sel:[1,0]
	v_mov_b32_e32 v139, v137
	v_fmac_f32_e32 v115, 0xba000000, v99
	v_fmac_f32_e32 v116, 0xba000000, v99
	v_mul_f32_e32 v84, v114, v114
	v_pk_add_f32 v[136:137], v[140:141], v[138:139]
	v_fmac_f32_e32 v117, 0xba000000, v99
	v_pk_fma_f32 v[138:139], v[114:115], v[114:115], v[84:85] op_sel_hi:[1,1,0]
	v_mul_f32_e32 v84, v116, v116
	v_pk_add_f32 v[136:137], v[136:137], v[136:137] op_sel_hi:[0,1]
	v_pk_fma_f32 v[140:141], v[116:117], v[116:117], v[84:85] op_sel_hi:[1,1,0]
	v_fmac_f32_e32 v97, 0xba000000, v99
	v_fmac_f32_e32 v96, 0xba000000, v99
	v_fmac_f32_e32 v113, 0xba000000, v99
	v_fmac_f32_e32 v112, 0xba000000, v99
	v_mul_f32_e32 v138, v112, v112
	v_mul_f32_e32 v140, v113, v113
	v_mul_f32_e32 v136, v96, v96
	v_mul_f32_e32 v84, v97, v97
	v_pk_add_f32 v[138:139], v[138:139], v[140:141]
	v_pk_add_f32 v[84:85], v[136:137], v[84:85]
	v_fmac_f32_e32 v93, 0xba000000, v99
	v_pk_add_f32 v[84:85], v[138:139], v[84:85]
	v_fmac_f32_e32 v92, 0xba000000, v99
	v_fmac_f32_e32 v95, 0xba000000, v99
	v_fmac_f32_e32 v94, 0xba000000, v99
	v_pk_add_f32 v[84:85], v[84:85], v[84:85] op_sel_hi:[0,1]
	v_pk_mul_f32 v[136:137], v[94:95], v[94:95]
	v_pk_mul_f32 v[138:139], v[92:93], v[92:93]
	v_fmac_f32_e32 v88, 0xba000000, v99
	v_pk_mov_b32 v[140:141], v[138:139], v[136:137] op_sel:[1,0]
	v_mov_b32_e32 v139, v137
	v_fmac_f32_e32 v89, 0xba000000, v99
	v_fmac_f32_e32 v90, 0xba000000, v99
	v_mul_f32_e32 v84, v88, v88
	v_pk_add_f32 v[136:137], v[140:141], v[138:139]
	v_fmac_f32_e32 v91, 0xba000000, v99
	v_pk_fma_f32 v[138:139], v[88:89], v[88:89], v[84:85] op_sel_hi:[1,1,0]
	v_mul_f32_e32 v84, v90, v90
	v_pk_add_f32 v[136:137], v[136:137], v[136:137] op_sel_hi:[0,1]
	v_pk_fma_f32 v[140:141], v[90:91], v[90:91], v[84:85] op_sel_hi:[1,1,0]
	v_fmac_f32_e32 v83, 0xba000000, v99
	v_fmac_f32_e32 v82, 0xba000000, v99
	v_fmac_f32_e32 v87, 0xba000000, v99
	v_fmac_f32_e32 v86, 0xba000000, v99
	v_mul_f32_e32 v138, v86, v86
	v_mul_f32_e32 v140, v87, v87
	v_mul_f32_e32 v136, v82, v82
	v_mul_f32_e32 v84, v83, v83
	v_pk_add_f32 v[138:139], v[138:139], v[140:141]
	v_pk_add_f32 v[84:85], v[136:137], v[84:85]
	v_ashrrev_i32_e32 v99, 31, v98
	v_pk_add_f32 v[84:85], v[138:139], v[84:85]
	v_lshlrev_b64 v[98:99], 13, v[98:99]
	v_add_f32_e32 v84, v84, v85
	ds_bpermute_b32 v85, v130, v84
	v_lshl_add_u64 v[136:137], s[0:1], 0, v[98:99]
	s_waitcnt lgkmcnt(0)
; __device__ __forceinline__ float wave_sum(float v, int lane) { for (int o = 32; o >= 1; o >>= 1) v += shflx(v, o, lane); return v; }
; __device__ __forceinline__ void ln_final(const bf16_t* tb, float* out, const float* __restrict__ g, const float* __restrict__ b, const int tid, const int bid) {
;     ...
;         const int rn = row + gridDim.x * 8;
;         if (rn < M) {
; #pragma unroll
;             for (int i = 0; i < 4; ++i) wn[i] = *(const u32x4*)(tb + (size_t)rn * D + i * 512 + lane * 8);
;         }
;     ...
;         const float rstd = __builtin_amdgcn_rsqf(wave_sum(q, lane) * (1.f / D) + LN_EPS);
; #pragma unroll
;         for (int i = 0; i < 8; ++i) {
;             const int c = (i >> 1) * 512 + lane * 8 + (i & 1) * 4;
;             const f32x4 gg = *(const f32x4*)(g + c), bb = *(const f32x4*)(b + c);
;             *(f32x4*)(out + (size_t)row * D + c) = (v[i] - mean) * rstd * gg + bb;
;         }
;     }
	v_add_f32_e32 v84, v84, v85
	ds_bpermute_b32 v85, v131, v84
	s_waitcnt lgkmcnt(0)
	v_add_f32_e32 v84, v84, v85
	ds_bpermute_b32 v85, v132, v84
	s_waitcnt lgkmcnt(0)
	v_add_f32_e32 v84, v84, v85
	ds_bpermute_b32 v85, v133, v84
	s_waitcnt lgkmcnt(0)
	v_add_f32_e32 v84, v84, v85
	ds_bpermute_b32 v85, v134, v84
	s_waitcnt lgkmcnt(0)
	v_add_f32_e32 v84, v84, v85
	ds_bpermute_b32 v85, v135, v84
	s_waitcnt lgkmcnt(0)
	v_add_f32_e32 v84, v84, v85
	v_fmamk_f32 v84, v84, 0x3a000000, v204
	v_rsq_f32_e32 v84, v84
	s_nop 0
	v_pk_mul_f32 v[98:99], v[126:127], v[84:85] op_sel_hi:[1,0]
	v_pk_mul_f32 v[126:127], v[128:129], v[84:85] op_sel_hi:[1,0]
	v_pk_mul_f32 v[122:123], v[122:123], v[84:85] op_sel_hi:[1,0]
	v_pk_mul_f32 v[124:125], v[124:125], v[84:85] op_sel_hi:[1,0]
	v_pk_mul_f32 v[118:119], v[118:119], v[84:85] op_sel_hi:[1,0]
	v_pk_mul_f32 v[120:121], v[120:121], v[84:85] op_sel_hi:[1,0]
	v_pk_mul_f32 v[114:115], v[114:115], v[84:85] op_sel_hi:[1,0]
	v_pk_mul_f32 v[116:117], v[116:117], v[84:85] op_sel_hi:[1,0]
	v_pk_fma_f32 v[128:129], v[8:9], v[126:127], v[16:17]
	v_pk_fma_f32 v[126:127], v[6:7], v[98:99], v[14:15]
	v_lshl_add_u64 v[98:99], v[136:137], 0, v[0:1]
	v_pk_fma_f32 v[124:125], v[4:5], v[124:125], v[12:13]
	v_pk_fma_f32 v[122:123], v[2:3], v[122:123], v[10:11]
	v_pk_fma_f32 v[120:121], v[24:25], v[120:121], v[32:33]
	v_pk_fma_f32 v[118:119], v[22:23], v[118:119], v[30:31]
	v_pk_fma_f32 v[116:117], v[20:21], v[116:117], v[28:29]
	v_pk_fma_f32 v[114:115], v[18:19], v[114:115], v[26:27]
	v_pk_mul_f32 v[112:113], v[112:113], v[84:85] op_sel_hi:[1,0]
	v_pk_mul_f32 v[96:97], v[96:97], v[84:85] op_sel_hi:[1,0]
	global_store_dwordx4 v[98:99], v[126:129], off
	global_store_dwordx4 v[98:99], v[122:125], off offset:16
	global_store_dwordx4 v[98:99], v[118:121], off offset:2048
	global_store_dwordx4 v[98:99], v[114:117], off offset:2064
	v_pk_fma_f32 v[98:99], v[40:41], v[96:97], v[48:49]
	v_pk_fma_f32 v[96:97], v[38:39], v[112:113], v[46:47]
	v_lshl_add_u64 v[112:113], v[136:137], 0, v[102:103]
	v_pk_mul_f32 v[92:93], v[92:93], v[84:85] op_sel_hi:[1,0]
	v_pk_mul_f32 v[94:95], v[94:95], v[84:85] op_sel_hi:[1,0]
	global_store_dwordx4 v[112:113], v[96:99], off
	v_pk_fma_f32 v[94:95], v[36:37], v[94:95], v[44:45]
	v_pk_fma_f32 v[92:93], v[34:35], v[92:93], v[42:43]
	v_lshl_add_u64 v[96:97], v[136:137], 0, v[104:105]
	v_pk_mul_f32 v[88:89], v[88:89], v[84:85] op_sel_hi:[1,0]
	v_pk_mul_f32 v[90:91], v[90:91], v[84:85] op_sel_hi:[1,0]
	v_pk_mul_f32 v[86:87], v[86:87], v[84:85] op_sel_hi:[1,0]
	v_pk_mul_f32 v[82:83], v[82:83], v[84:85] op_sel_hi:[1,0]
	global_store_dwordx4 v[96:97], v[92:95], off
	v_pk_fma_f32 v[90:91], v[56:57], v[90:91], v[64:65]
	v_pk_fma_f32 v[88:89], v[54:55], v[88:89], v[62:63]
	v_lshl_add_u64 v[92:93], v[136:137], 0, v[106:107]
	v_pk_fma_f32 v[84:85], v[52:53], v[82:83], v[60:61]
	v_pk_fma_f32 v[82:83], v[50:51], v[86:87], v[58:59]
	v_lshl_add_u64 v[86:87], v[136:137], 0, v[108:109]
	global_store_dwordx4 v[92:93], v[88:91], off
	global_store_dwordx4 v[86:87], v[82:85], off
	s_waitcnt vmcnt(8)
	v_mov_b64_e32 v[92:93], v[76:77]
	v_mov_b64_e32 v[88:89], v[72:73]
	v_mov_b64_e32 v[84:85], v[68:69]
	v_mov_b64_e32 v[96:97], v[80:81]
	v_mov_b64_e32 v[82:83], v[66:67]
	v_mov_b64_e32 v[86:87], v[70:71]
	v_mov_b64_e32 v[90:91], v[74:75]
	v_mov_b64_e32 v[94:95], v[78:79]
	v_mov_b32_e32 v98, v110
	s_andn2_b64 exec, exec, s[6:7]
	s_cbranch_execz .LBB0_95
.LBB0_93:
	v_add_u32_e32 v110, s92, v98
	s_movk_i32 s2, 0x3fff
	v_cmp_gt_i32_e64 s[0:1], s60, v110
	v_cmp_lt_i32_e32 vcc, s2, v110
	s_and_saveexec_b64 s[8:9], s[0:1]
	s_cbranch_execz .LBB0_92
	v_ashrrev_i32_e32 v111, 31, v110
	v_lshlrev_b64 v[66:67], 12, v[110:111]
	v_lshl_add_u64 v[66:67], v[100:101], 0, v[66:67]
	global_load_dwordx4 v[78:81], v[66:67], off
	global_load_dwordx4 v[74:77], v[66:67], off offset:1024
	global_load_dwordx4 v[70:73], v[66:67], off offset:2048
	s_nop 0
	global_load_dwordx4 v[66:69], v[66:67], off offset:3072
	s_branch .LBB0_92
